# seam: the XCD's last arriver issues its own L1 invalidate behind the cross-XCD arrival atomic instead of before it
# speedup vs baseline: 1.0079x; 1.0079x over previous
; __device__ __forceinline__ unsigned xb_ld(unsigned* p)              { return __hip_atomic_load(p, __ATOMIC_RELAXED, __HIP_MEMORY_SCOPE_AGENT); }
; __device__ __forceinline__ unsigned xb_add(unsigned* p, unsigned v) { return __hip_atomic_fetch_add(p, v, __ATOMIC_RELAXED, __HIP_MEMORY_SCOPE_AGENT); }
; #define XB_SPIN(cond, bar) do { unsigned _sp = 0; while (cond) { __builtin_amdgcn_s_sleep(1); \
;     if ((++_sp & 255u) == 0u) { if (xb_ld(&(bar)[XB_TMO])) break; if (_sp > XB_SPIN_CAP) { atomicAdd(&(bar)[XB_TMO], 1u); break; } } } } while (0)
; __device__ __forceinline__ void xcd_barrier(const XcdBarrier& b) {
;     ...
;         const unsigned old = xb_add(&bar[XB_XSUB(b.x)], 1u);
;         const unsigned gen = old / nloc;
;         if (old + 1u == (gen + 1u) * nloc) {
;             __builtin_amdgcn_fence(__ATOMIC_RELEASE, "agent");
;             asm volatile("s_waitcnt vmcnt(0)" ::: "memory");
;             const unsigned og = xb_add(&bar[XB_TOP], 1u);
;             const unsigned tg = og / nx;
;             if (og + 1u == (tg + 1u) * nx) xb_add(&bar[XB_TOPGEN], 1u);
;             else XB_SPIN(xb_ld(&bar[XB_TOPGEN]) == tg, bar);
;             __builtin_amdgcn_fence(__ATOMIC_ACQUIRE, "agent");
.LBB0_87:
	s_or_b64 exec, exec, s[10:11]
	buffer_inv sc1
	s_waitcnt vmcnt(0)
	v_readfirstlane_b32 s0, v2
	s_add_u32 s12, s86, 0x3400
	s_addc_u32 s13, s87, 0
	v_add_u32_e32 v1, s0, v1
	v_add_u32_e32 v4, 1, v1
	s_mov_b64 s[0:1], 0
	v_readlane_b32 s10, v244, 63
	s_nop 0
	v_mul_u32_u24_e32 v0, s10, v0
	v_cmp_ne_u32_e32 vcc, v4, v0
	v_mov_b32_e32 v3, v0
	v_mov_b64_e32 v[0:1], s[12:13]
	s_and_saveexec_b64 s[10:11], vcc
	s_cbranch_execz .LBB0_99
	v_mov_b32_e32 v0, 0
	global_load_dword v1, v0, s[12:13] sc1
	s_mov_b64 s[0:1], 0
	s_waitcnt vmcnt(0)
	v_cmp_lt_u32_e32 vcc, v1, v3
	s_and_saveexec_b64 s[16:17], vcc
	s_cbranch_execz .LBB0_98
	s_add_u32 s14, s86, 0x200
	s_addc_u32 s15, s87, 0
	s_mov_b32 s3, 1
	s_mov_b64 s[18:19], 0
	s_branch .LBB0_91

; __device__ __forceinline__ unsigned xb_ld(unsigned* p)              { return __hip_atomic_load(p, __ATOMIC_RELAXED, __HIP_MEMORY_SCOPE_AGENT); }
; __device__ __forceinline__ unsigned xb_add(unsigned* p, unsigned v) { return __hip_atomic_fetch_add(p, v, __ATOMIC_RELAXED, __HIP_MEMORY_SCOPE_AGENT); }
; #define XB_SPIN(cond, bar) do { unsigned _sp = 0; while (cond) { __builtin_amdgcn_s_sleep(1); \
;     if ((++_sp & 255u) == 0u) { if (xb_ld(&(bar)[XB_TMO])) break; if (_sp > XB_SPIN_CAP) { atomicAdd(&(bar)[XB_TMO], 1u); break; } } } } while (0)
; __device__ __forceinline__ void xcd_barrier(const XcdBarrier& b) {
;     ...
;         const unsigned old = xb_add(&bar[XB_XSUB(b.x)], 1u);
;         const unsigned gen = old / nloc;
;         if (old + 1u == (gen + 1u) * nloc) {
;             __builtin_amdgcn_fence(__ATOMIC_RELEASE, "agent");
;             asm volatile("s_waitcnt vmcnt(0)" ::: "memory");
;             const unsigned og = xb_add(&bar[XB_TOP], 1u);
;             const unsigned tg = og / nx;
;             if (og + 1u == (tg + 1u) * nx) xb_add(&bar[XB_TOPGEN], 1u);
;             else XB_SPIN(xb_ld(&bar[XB_TOPGEN]) == tg, bar);
;             __builtin_amdgcn_fence(__ATOMIC_ACQUIRE, "agent");
.LBB0_1828:
	s_or_b64 exec, exec, s[8:9]
	buffer_inv sc1
	s_waitcnt vmcnt(0)
	v_readfirstlane_b32 s0, v2
	s_add_u32 s10, s86, 0x3400
	s_addc_u32 s11, s87, 0
	v_add_u32_e32 v1, s0, v1
	v_add_u32_e32 v4, 1, v1
	s_mov_b64 s[0:1], 0
	v_readlane_b32 s8, v244, 63
	s_nop 0
	v_mul_u32_u24_e32 v0, s8, v0
	v_cmp_ne_u32_e32 vcc, v4, v0
	v_mov_b32_e32 v3, v0
	v_mov_b64_e32 v[0:1], s[10:11]
	s_and_saveexec_b64 s[8:9], vcc
	s_cbranch_execz .LBB0_1840
	v_mov_b32_e32 v0, 0
	global_load_dword v1, v0, s[10:11] sc1
	s_mov_b64 s[0:1], 0
	s_waitcnt vmcnt(0)
	v_cmp_lt_u32_e32 vcc, v1, v3
	s_and_saveexec_b64 s[14:15], vcc
	s_cbranch_execz .LBB0_1839
	s_add_u32 s12, s86, 0x200
	s_addc_u32 s13, s87, 0
	s_mov_b32 s3, 1
	s_mov_b64 s[16:17], 0
	s_branch .LBB0_1832

; __device__ __forceinline__ unsigned xb_ld(unsigned* p)              { return __hip_atomic_load(p, __ATOMIC_RELAXED, __HIP_MEMORY_SCOPE_AGENT); }
; __device__ __forceinline__ unsigned xb_add(unsigned* p, unsigned v) { return __hip_atomic_fetch_add(p, v, __ATOMIC_RELAXED, __HIP_MEMORY_SCOPE_AGENT); }
; #define XB_SPIN(cond, bar) do { unsigned _sp = 0; while (cond) { __builtin_amdgcn_s_sleep(1); \
;     if ((++_sp & 255u) == 0u) { if (xb_ld(&(bar)[XB_TMO])) break; if (_sp > XB_SPIN_CAP) { atomicAdd(&(bar)[XB_TMO], 1u); break; } } } } while (0)
; __device__ __forceinline__ void xcd_barrier(const XcdBarrier& b) {
;     ...
;         const unsigned old = xb_add(&bar[XB_XSUB(b.x)], 1u);
;         const unsigned gen = old / nloc;
;         if (old + 1u == (gen + 1u) * nloc) {
;             __builtin_amdgcn_fence(__ATOMIC_RELEASE, "agent");
;             asm volatile("s_waitcnt vmcnt(0)" ::: "memory");
;             const unsigned og = xb_add(&bar[XB_TOP], 1u);
;             const unsigned tg = og / nx;
;             if (og + 1u == (tg + 1u) * nx) xb_add(&bar[XB_TOPGEN], 1u);
;             else XB_SPIN(xb_ld(&bar[XB_TOPGEN]) == tg, bar);
;             __builtin_amdgcn_fence(__ATOMIC_ACQUIRE, "agent");
.LBB0_1953:
	s_or_b64 exec, exec, s[8:9]
	buffer_inv sc1
	s_waitcnt vmcnt(0)
	v_readfirstlane_b32 s0, v2
	s_add_u32 s10, s86, 0x3400
	s_addc_u32 s11, s87, 0
	v_add_u32_e32 v1, s0, v1
	v_add_u32_e32 v4, 1, v1
	s_mov_b64 s[0:1], 0
	v_readlane_b32 s8, v244, 63
	s_nop 0
	v_mul_u32_u24_e32 v0, s8, v0
	v_cmp_ne_u32_e32 vcc, v4, v0
	v_mov_b32_e32 v3, v0
	v_mov_b64_e32 v[0:1], s[10:11]
	s_and_saveexec_b64 s[8:9], vcc
	s_cbranch_execz .LBB0_1965
	v_mov_b32_e32 v0, 0
	global_load_dword v1, v0, s[10:11] sc1
	s_mov_b64 s[0:1], 0
	s_waitcnt vmcnt(0)
	v_cmp_lt_u32_e32 vcc, v1, v3
	s_and_saveexec_b64 s[14:15], vcc
	s_cbranch_execz .LBB0_1964
	s_add_u32 s12, s86, 0x200
	s_addc_u32 s13, s87, 0
	s_mov_b32 s24, 1
	s_mov_b64 s[16:17], 0
	s_branch .LBB0_1957
